# ROW_P1: row-invariant gain vectors preloaded once into registers (removes 16 serialized load+vmcnt(0) round trips per row) + MIX_O block-id rotation
# baseline (speedup 1.0000x reference)
; __device__ __forceinline__ unsigned char* WSP() { return (unsigned char*)IN(41); }
; __device__ __forceinline__ int TID() { int t = threadIdx.x; asm volatile("" : "+v"(t)); return t; }
; __device__ __forceinline__ int BID() { int b = blockIdx.x; asm volatile("" : "+s"(b)); return b; }
; __device__ __forceinline__ int GSZ() { int g = gridDim.x; asm volatile("" : "+s"(g)); return g; }
; __device__ __forceinline__ unsigned pk2(float lo, float hi) { f32x2c v = {lo, hi}; return __builtin_bit_cast(unsigned, __builtin_convertvector(v, bf16x2c)); }
; __device__ __forceinline__ int rfl(int v) { return __builtin_amdgcn_readfirstlane(v); }
; __device__ __forceinline__ void row_post1(const Params& p, int layer) {
;     const int tid_ = TID(), lane = tid_ & 63, wave_ = rfl(tid_ >> 6), bid_ = BID(), gw = bid_ * 8 + wave_, ngw = GSZ() * 8;
;     unsigned char* ws = WSP();
;     bf16_t* X = (bf16_t*)(ws + ((layer & 1) ? WS_XB : WS_XA));
;     const bf16_t* MIX = (const bf16_t*)(ws + WS_MIX);
;     const float* g1 = IN(8) + (size_t)layer * D; const float* g2 = IN(9) + (size_t)layer * D;
;     presum_sample_rows((bf16_t*)(ws + WS_MIX), bid_, tid_);
;     const int nit = (MP - gw + ngw - 1) / ngw;
;     for (int it_ = 0; it_ <= nit; ++it_) {
;         int m = gw + it_ * ngw;
;         if (it_ == nit) { if (wave_ >= 4 || bid_ >= MS / 4) break; m = MP + 4 * bid_ + wave_; }
;         f32x4 x[8], mx[8];
;         xrow_load(X, layer == 0, m, lane, x);
;         row_load_bf16(MIX + (size_t)m * D, lane, mx);
;         const float rs = row_rstd(mx);
; #pragma unroll
;         for (int j = 0; j < 8; ++j) { const f32x4 g = *(const f32x4*)(g1 + 256 * j + 4 * lane); x[j] += mx[j] * rs * g; u32x2 w; w.x = pk2(x[j][0], x[j][1]); w.y = pk2(x[j][2], x[j][3]); *(u32x2*)(X + (size_t)m * D + 256 * j + 4 * lane) = w; }
;         const float rs2 = row_rstd(x);
; #pragma unroll
;         for (int j = 0; j < 8; ++j) { const f32x4 g = *(const f32x4*)(g2 + 256 * j + 4 * lane); x[j] = x[j] * rs2 * g; }
.LBB0_984:
	s_lshl_b32 s5, s5, 3
	s_abs_i32 s15, s5
	v_cvt_f32_u32_e32 v1, s15
	s_ashr_i32 s12, s4, 6
	s_lshl_b32 s4, s14, 3
	s_add_i32 s4, s4, s12
	v_rcp_iflag_f32_e32 v1, v1
	s_sub_i32 s16, s5, s4
	s_add_i32 s17, s16, 0x1fff
	s_sub_i32 s16, 0xffffe001, s16
	v_mul_f32_e32 v1, 0x4f7ffffe, v1
	v_cvt_u32_f32_e32 v1, v1
	s_xor_b32 s13, s17, s5
	s_max_i32 s16, s17, s16
	s_sub_i32 s17, 0, s15
	v_readfirstlane_b32 s18, v1
	s_mul_i32 s17, s17, s18
	s_mul_hi_u32 s17, s18, s17
	s_add_i32 s18, s18, s17
	s_mul_hi_u32 s17, s16, s18
	s_mul_i32 s18, s17, s15
	s_sub_i32 s16, s16, s18
	s_ashr_i32 s13, s13, 31
	s_add_i32 s18, s17, 1
	s_sub_i32 s19, s16, s15
	s_cmp_ge_u32 s16, s15
	s_cselect_b32 s17, s18, s17
	s_cselect_b32 s16, s19, s16
	s_add_i32 s18, s17, 1
	s_cmp_ge_u32 s16, s15
	s_cselect_b32 s15, s18, s17
	s_xor_b32 s15, s15, s13
	s_sub_i32 s16, s15, s13
	s_cmp_lt_i32 s16, 0
	s_waitcnt lgkmcnt(0)
	s_barrier
	s_cbranch_scc1 .LBB0_997
	v_readlane_b32 s16, v234, 26
	s_add_u32 s16, s6, s16
	s_addc_u32 s17, s7, 0
	v_readlane_b32 s20, v234, 52
	v_readlane_b32 s21, v234, 53
	s_add_u32 s18, s2, s20
	s_addc_u32 s19, s3, s21
	s_add_u32 s10, s10, s20
	s_addc_u32 s11, s11, s21
	s_waitcnt vmcnt(0)
	v_and_b32_e32 v4, 0xfc, v0
	s_cmp_lt_i32 s12, 4
	v_lshlrev_b32_e32 v2, 1, v4
	s_cselect_b64 s[2:3], -1, 0
	v_lshl_add_u64 v[6:7], s[6:7], 0, v[2:3]
	s_mov_b64 s[6:7], 0x10d00000
	s_and_b64 s[2:3], s[2:3], s[8:9]
	s_lshl_b32 s8, s14, 2
	v_lshl_add_u64 v[0:1], s[16:17], 0, v[2:3]
	s_waitcnt vmcnt(0)
	v_lshl_add_u64 v[40:41], v[6:7], 0, s[6:7]
	v_lshlrev_b32_e32 v2, 2, v4
	s_mov_b64 s[6:7], 0xec00000
	s_add_i32 s12, s12, s8
	v_lshl_add_u64 v[42:43], s[18:19], 0, v[2:3]
	v_lshl_add_u64 v[44:45], s[10:11], 0, v[2:3]
	v_lshl_add_u64 v[46:47], v[6:7], 0, s[6:7]
	s_mov_b64 s[6:7], 0x1400
	s_mov_b64 s[8:9], 0x1800
	s_mov_b64 s[10:11], 0x1c00
	s_addk_i32 s12, 0x2000
	v_lshl_add_u64 v[48:49], v[42:43], 0, s[56:57]
	v_lshl_add_u64 v[50:51], v[42:43], 0, s[6:7]
	v_lshl_add_u64 v[52:53], v[42:43], 0, s[8:9]
	v_lshl_add_u64 v[54:55], v[42:43], 0, s[10:11]
	v_lshl_add_u64 v[56:57], v[44:45], 0, s[56:57]
	v_lshl_add_u64 v[58:59], v[44:45], 0, s[6:7]
	v_lshl_add_u64 v[60:61], v[44:45], 0, s[8:9]
	v_lshl_add_u64 v[62:63], v[44:45], 0, s[10:11]
	s_sub_i32 s13, s13, s15
	v_lshlrev_b32_e32 v2, 2, v4
	global_load_dwordx4 v[160:163], v[42:43], off
	global_load_dwordx4 v[164:167], v[42:43], off offset:1024
	global_load_dwordx4 v[168:171], v[42:43], off offset:2048
	global_load_dwordx4 v[172:175], v[42:43], off offset:3072
	global_load_dwordx4 v[176:179], v[48:49], off
	global_load_dwordx4 v[180:183], v[50:51], off
	global_load_dwordx4 v[184:187], v[52:53], off
	global_load_dwordx4 v[188:191], v[54:55], off
	global_load_dwordx4 v[192:195], v[44:45], off
	global_load_dwordx4 v[196:199], v[44:45], off offset:1024
	global_load_dwordx4 v[200:203], v[44:45], off offset:2048
	global_load_dwordx4 v[204:207], v[44:45], off offset:3072
	global_load_dwordx4 v[208:211], v[56:57], off
	global_load_dwordx4 v[212:215], v[58:59], off
	global_load_dwordx4 v[216:219], v[60:61], off
	global_load_dwordx4 v[220:223], v[62:63], off
	s_branch .LBB0_989

; __device__ __forceinline__ void row_load_bf16(const bf16_t* p, int lane, f32x4 (&v)[8]) {
; #pragma unroll
;     for (int j = 0; j < 8; ++j) { const u32x2 r = *(const u32x2*)(p + 256 * j + 4 * lane);
;         v[j][0] = __builtin_bit_cast(float, r.x << 16); v[j][1] = __builtin_bit_cast(float, r.x & 0xffff0000u); v[j][2] = __builtin_bit_cast(float, r.y << 16); v[j][3] = __builtin_bit_cast(float, r.y & 0xffff0000u); }
; }
; __device__ __forceinline__ float row_rstd(const f32x4 (&v)[8]) {
;     float s = 0.f;
; #pragma unroll
;     for (int j = 0; j < 8; ++j) s += (v[j][0] * v[j][0] + v[j][1] * v[j][1]) + (v[j][2] * v[j][2] + v[j][3] * v[j][3]);
;     return rsqrtf(wave_sum(s) * (1.f / D) + 1e-6f);
; __device__ __forceinline__ void row_post1(const Params& p, int layer) {
;     ...
;         row_load_bf16(MIX + (size_t)m * D, lane, mx);
;         const float rs = row_rstd(mx);
.LBB0_987:
	s_lshl_b64 s[6:7], s[6:7], 12
	v_lshl_add_u64 v[36:37], v[40:41], 0, s[6:7]
	global_load_dwordx2 v[38:39], v[36:37], off
	global_load_dwordx2 v[76:77], v[36:37], off offset:512
	global_load_dwordx2 v[78:79], v[36:37], off offset:1024
	global_load_dwordx2 v[64:65], v[36:37], off offset:1536
	global_load_dwordx2 v[80:81], v[36:37], off offset:2048
	global_load_dwordx2 v[100:101], v[36:37], off offset:2560
	global_load_dwordx2 v[102:103], v[36:37], off offset:3072
	s_nop 0
	global_load_dwordx2 v[36:37], v[36:37], off offset:3584
	s_add_i32 s13, s13, 1
	s_add_i32 s4, s4, s5
	s_cmp_eq_u32 s13, 1
	s_waitcnt vmcnt(7)
	v_and_b32_e32 v97, 0xffff0000, v38
	v_and_b32_e32 v99, 0xffff0000, v39
	v_lshlrev_b32_e32 v96, 16, v38
	v_lshlrev_b32_e32 v98, 16, v39
	s_waitcnt vmcnt(0)
	v_lshlrev_b32_e32 v69, 16, v36
	v_and_b32_e32 v67, 0xffff0000, v36
	v_mul_f32_e32 v36, v99, v99
	v_and_b32_e32 v93, 0xffff0000, v77
	v_and_b32_e32 v92, 0xffff0000, v76
	v_mul_f32_e32 v66, v97, v97
	v_lshlrev_b32_e32 v75, 16, v64
	v_and_b32_e32 v73, 0xffff0000, v64
	v_lshlrev_b32_e32 v70, 16, v65
	v_and_b32_e32 v71, 0xffff0000, v65
	v_lshlrev_b32_e32 v64, 16, v37
	v_and_b32_e32 v65, 0xffff0000, v37
	v_pk_fma_f32 v[36:37], v[98:99], v[98:99], v[36:37] op_sel_hi:[1,1,0]
	v_lshlrev_b32_e32 v95, 16, v77
	v_lshlrev_b32_e32 v94, 16, v76
	v_pk_mul_f32 v[38:39], v[92:93], v[92:93]
	v_pk_fma_f32 v[76:77], v[96:97], v[96:97], v[66:67] op_sel_hi:[1,1,0]
	v_pk_fma_f32 v[38:39], v[94:95], v[94:95], v[38:39]
	v_lshlrev_b32_e32 v88, 16, v78
	v_and_b32_e32 v89, 0xffff0000, v78
	v_lshlrev_b32_e32 v90, 16, v79
	v_and_b32_e32 v91, 0xffff0000, v79
	v_mov_b32_e32 v74, v76
	v_mov_b32_e32 v78, v36
	v_mov_b32_e32 v79, v75
	v_mul_f32_e32 v68, v73, v73
	v_pk_add_f32 v[36:37], v[76:77], v[36:37]
	v_pk_mul_f32 v[76:77], v[74:75], v[78:79]
	v_pk_add_f32 v[38:39], v[38:39], v[38:39] op_sel:[0,1] op_sel_hi:[1,0]
	v_mov_b32_e32 v37, v77
	v_mov_b32_e32 v39, v68
	v_pk_add_f32 v[36:37], v[36:37], v[38:39]
	v_mul_f32_e32 v38, v89, v89
	v_mul_f32_e32 v66, v91, v91
	v_mul_f32_e32 v72, v70, v70
	v_mul_f32_e32 v82, v71, v71
	v_pk_fma_f32 v[38:39], v[88:89], v[88:89], v[38:39] op_sel_hi:[1,1,0]
	v_pk_fma_f32 v[76:77], v[90:91], v[90:91], v[66:67] op_sel_hi:[1,1,0]
	v_mov_b32_e32 v39, v72
	v_mov_b32_e32 v77, v82
	v_pk_add_f32 v[38:39], v[38:39], v[76:77]
	v_and_b32_e32 v85, 0xffff0000, v81
	v_and_b32_e32 v84, 0xffff0000, v80
	v_pk_add_f32 v[36:37], v[36:37], v[38:39]
	v_lshlrev_b32_e32 v87, 16, v81
	v_lshlrev_b32_e32 v86, 16, v80
	v_pk_mul_f32 v[38:39], v[84:85], v[84:85]
	v_and_b32_e32 v81, 0xffff0000, v101
	v_pk_fma_f32 v[38:39], v[86:87], v[86:87], v[38:39]
	v_and_b32_e32 v80, 0xffff0000, v100
	v_pk_add_f32 v[38:39], v[38:39], v[38:39] op_sel:[0,1] op_sel_hi:[1,0]
	v_lshlrev_b32_e32 v83, 16, v101
	v_lshlrev_b32_e32 v82, 16, v100
	v_pk_mul_f32 v[76:77], v[80:81], v[80:81]
	v_pk_add_f32 v[36:37], v[36:37], v[36:37] op_sel:[0,1] op_sel_hi:[1,0]
	v_pk_fma_f32 v[100:101], v[82:83], v[82:83], v[76:77]
	v_lshlrev_b32_e32 v76, 16, v102
	v_and_b32_e32 v77, 0xffff0000, v102
	v_lshlrev_b32_e32 v78, 16, v103
	v_and_b32_e32 v79, 0xffff0000, v103
	v_mov_b32_e32 v68, v36
	v_mov_b32_e32 v102, v38
	v_mov_b32_e32 v103, v69
	v_pk_add_f32 v[36:37], v[36:37], v[38:39]
	v_pk_mul_f32 v[38:39], v[68:69], v[102:103]
	v_mul_f32_e32 v66, v67, v67
	v_mov_b32_e32 v37, v39
	v_pk_add_f32 v[38:39], v[100:101], v[100:101] op_sel:[0,1] op_sel_hi:[1,0]
	v_mul_f32_e32 v72, v64, v64
	v_mov_b32_e32 v39, v66
	v_pk_add_f32 v[36:37], v[36:37], v[38:39]
	v_mul_f32_e32 v38, v77, v77
	v_mul_f32_e32 v66, v79, v79
	v_mul_f32_e32 v74, v65, v65
	v_pk_fma_f32 v[38:39], v[76:77], v[76:77], v[38:39] op_sel_hi:[1,1,0]
	v_pk_fma_f32 v[100:101], v[78:79], v[78:79], v[66:67] op_sel_hi:[1,1,0]
	v_mov_b32_e32 v39, v72
	v_mov_b32_e32 v101, v74
	v_pk_add_f32 v[38:39], v[38:39], v[100:101]
	v_lshl_add_u64 v[100:101], v[0:1], 0, s[6:7]
	v_pk_add_f32 v[36:37], v[36:37], v[38:39]
	v_xor_b32_e32 v38, 1, v152
	v_add_f32_e32 v36, v36, v37
	v_and_b32_e32 v37, 64, v152
	v_add_u32_e32 v37, 64, v37
	v_cmp_lt_i32_e32 vcc, v38, v37
	v_mov_b32_e32 v72, v75
	v_mov_b32_e32 v66, v69
	v_cndmask_b32_e32 v38, v152, v38, vcc
	v_lshlrev_b32_e32 v74, 2, v38
	ds_bpermute_b32 v38, v74, v36
	s_waitcnt lgkmcnt(0)
	v_add_f32_e32 v36, v36, v38
	v_xor_b32_e32 v38, 2, v152
	v_cmp_lt_i32_e32 vcc, v38, v37
	s_nop 1
	v_cndmask_b32_e32 v38, v152, v38, vcc
	v_lshlrev_b32_e32 v102, 2, v38
	ds_bpermute_b32 v38, v102, v36
	s_waitcnt lgkmcnt(0)
	v_add_f32_e32 v36, v36, v38
	v_xor_b32_e32 v38, 4, v152
	v_cmp_lt_i32_e32 vcc, v38, v37
	s_nop 1
	v_cndmask_b32_e32 v38, v152, v38, vcc
	v_lshlrev_b32_e32 v103, 2, v38
	ds_bpermute_b32 v38, v103, v36
	s_waitcnt lgkmcnt(0)
	v_add_f32_e32 v36, v36, v38
	v_xor_b32_e32 v38, 8, v152
	v_cmp_lt_i32_e32 vcc, v38, v37
	s_nop 1
	v_cndmask_b32_e32 v38, v152, v38, vcc
	v_lshlrev_b32_e32 v104, 2, v38
	ds_bpermute_b32 v38, v104, v36
	s_waitcnt lgkmcnt(0)
	v_add_f32_e32 v36, v36, v38
	v_xor_b32_e32 v38, 16, v152
	v_cmp_lt_i32_e32 vcc, v38, v37
	s_nop 1
	v_cndmask_b32_e32 v38, v152, v38, vcc
	v_lshlrev_b32_e32 v105, 2, v38
	ds_bpermute_b32 v38, v105, v36
	s_waitcnt lgkmcnt(0)
	v_add_f32_e32 v36, v36, v38
	v_xor_b32_e32 v38, 32, v152
	v_cmp_lt_i32_e32 vcc, v38, v37
	s_nop 1
	v_cndmask_b32_e32 v37, v152, v38, vcc
	v_lshlrev_b32_e32 v106, 2, v37
	ds_bpermute_b32 v37, v106, v36
	s_waitcnt lgkmcnt(0)
; __device__ __forceinline__ unsigned pk2(float lo, float hi) { f32x2c v = {lo, hi}; return __builtin_bit_cast(unsigned, __builtin_convertvector(v, bf16x2c)); }
; __device__ __forceinline__ void row_post1(const Params& p, int layer) {
;     ...
;         const float rs = row_rstd(mx);
; #pragma unroll
;         for (int j = 0; j < 8; ++j) { const f32x4 g = *(const f32x4*)(g1 + 256 * j + 4 * lane); x[j] += mx[j] * rs * g; u32x2 w; w.x = pk2(x[j][0], x[j][1]); w.y = pk2(x[j][2], x[j][3]); *(u32x2*)(X + (size_t)m * D + 256 * j + 4 * lane) = w; }
;         const float rs2 = row_rstd(x);
; #pragma unroll
;         for (int j = 0; j < 8; ++j) { const f32x4 g = *(const f32x4*)(g2 + 256 * j + 4 * lane); x[j] = x[j] * rs2 * g; }
	v_add_f32_e32 v36, v36, v37
	v_fmamk_f32 v36, v36, 0x3a000000, v147
	v_cmp_gt_f32_e32 vcc, s29, v36
	v_mul_f32_e32 v37, 0x4b800000, v36
	s_nop 0
	v_cndmask_b32_e32 v36, v36, v37, vcc
	v_rsq_f32_e32 v36, v36
	s_nop 0
	v_mul_f32_e32 v37, 0x45800000, v36
	v_cndmask_b32_e32 v68, v36, v37, vcc
	v_pk_mul_f32 v[96:97], v[68:69], v[96:97] op_sel_hi:[0,1]
	v_pk_mul_f32 v[98:99], v[68:69], v[98:99] op_sel_hi:[0,1]
	v_pk_mul_f32 v[88:89], v[68:69], v[88:89] op_sel_hi:[0,1]
	v_pk_mul_f32 v[90:91], v[68:69], v[90:91] op_sel_hi:[0,1]
	v_pk_mul_f32 v[72:73], v[68:69], v[72:73] op_sel_hi:[0,1]
	v_pk_mul_f32 v[70:71], v[68:69], v[70:71] op_sel_hi:[0,1]
	v_pk_mul_f32 v[66:67], v[68:69], v[66:67] op_sel_hi:[0,1]
	v_pk_mul_f32 v[64:65], v[68:69], v[64:65] op_sel_hi:[0,1]
	v_pk_fma_f32 v[34:35], v[162:163], v[98:99], v[34:35]
	v_pk_fma_f32 v[32:33], v[160:161], v[96:97], v[32:33]
	v_cvt_pk_bf16_f32 v37, v34, v35
	v_cvt_pk_bf16_f32 v36, v32, v33
	global_store_dwordx2 v[100:101], v[36:37], off
	v_mov_b32_e32 v96, v94
	v_mov_b32_e32 v97, v92
	v_mov_b32_e32 v92, v95
	v_pk_mul_f32 v[96:97], v[68:69], v[96:97] op_sel_hi:[0,1]
	v_pk_mul_f32 v[92:93], v[68:69], v[92:93] op_sel_hi:[0,1]
	v_pk_fma_f32 v[30:31], v[166:167], v[92:93], v[30:31]
	v_pk_fma_f32 v[28:29], v[164:165], v[96:97], v[28:29]
	v_cvt_pk_bf16_f32 v37, v30, v31
	v_cvt_pk_bf16_f32 v36, v28, v29
	global_store_dwordx2 v[100:101], v[36:37], off offset:512
	v_pk_fma_f32 v[26:27], v[170:171], v[90:91], v[26:27]
	v_pk_fma_f32 v[24:25], v[168:169], v[88:89], v[24:25]
	v_cvt_pk_bf16_f32 v37, v26, v27
	v_cvt_pk_bf16_f32 v36, v24, v25
	global_store_dwordx2 v[100:101], v[36:37], off offset:1024
	v_pk_fma_f32 v[22:23], v[174:175], v[70:71], v[22:23]
	v_pk_fma_f32 v[20:21], v[172:173], v[72:73], v[20:21]
	v_cvt_pk_bf16_f32 v37, v22, v23
	v_cvt_pk_bf16_f32 v36, v20, v21
	global_store_dwordx2 v[100:101], v[36:37], off offset:1536
	v_mov_b32_e32 v70, v86
	v_mov_b32_e32 v71, v84
	v_mov_b32_e32 v84, v87
	v_pk_mul_f32 v[70:71], v[68:69], v[70:71] op_sel_hi:[0,1]
	v_pk_mul_f32 v[72:73], v[68:69], v[84:85] op_sel_hi:[0,1]
	v_pk_fma_f32 v[18:19], v[178:179], v[72:73], v[18:19]
	v_pk_fma_f32 v[16:17], v[176:177], v[70:71], v[16:17]
	v_cvt_pk_bf16_f32 v37, v18, v19
	v_cvt_pk_bf16_f32 v36, v16, v17
	global_store_dwordx2 v[100:101], v[36:37], off offset:2048
	v_mov_b32_e32 v70, v82
	v_mov_b32_e32 v71, v80
	v_mov_b32_e32 v80, v83
	v_pk_mul_f32 v[70:71], v[68:69], v[70:71] op_sel_hi:[0,1]
	v_pk_mul_f32 v[72:73], v[68:69], v[80:81] op_sel_hi:[0,1]
	v_pk_fma_f32 v[14:15], v[182:183], v[72:73], v[14:15]
	v_pk_fma_f32 v[12:13], v[180:181], v[70:71], v[12:13]
	v_cvt_pk_bf16_f32 v37, v14, v15
	v_cvt_pk_bf16_f32 v36, v12, v13
	global_store_dwordx2 v[100:101], v[36:37], off offset:2560
	v_pk_mul_f32 v[70:71], v[68:69], v[76:77] op_sel_hi:[0,1]
	v_pk_mul_f32 v[72:73], v[68:69], v[78:79] op_sel_hi:[0,1]
	v_pk_fma_f32 v[10:11], v[186:187], v[72:73], v[10:11]
	v_pk_fma_f32 v[8:9], v[184:185], v[70:71], v[8:9]
	v_cvt_pk_bf16_f32 v37, v10, v11
	v_cvt_pk_bf16_f32 v36, v8, v9
	global_store_dwordx2 v[100:101], v[36:37], off offset:3072
	v_pk_fma_f32 v[6:7], v[190:191], v[64:65], v[6:7]
	v_pk_fma_f32 v[4:5], v[188:189], v[66:67], v[4:5]
	v_cvt_pk_bf16_f32 v37, v6, v7
	v_cvt_pk_bf16_f32 v36, v4, v5
	v_mov_b32_e32 v38, v33
	v_mov_b32_e32 v39, v29
	global_store_dwordx2 v[100:101], v[36:37], off offset:3584
	v_mov_b32_e32 v36, v32
	v_mov_b32_e32 v37, v28
	v_pk_mul_f32 v[38:39], v[38:39], v[38:39]
	v_mov_b32_e32 v64, v35
	v_mov_b32_e32 v65, v31
	v_pk_fma_f32 v[36:37], v[36:37], v[36:37], v[38:39]
	v_mov_b32_e32 v38, v34
	v_mov_b32_e32 v39, v30
	v_pk_mul_f32 v[64:65], v[64:65], v[64:65]
	s_nop 0
	v_pk_fma_f32 v[38:39], v[38:39], v[38:39], v[64:65]
	v_pk_mul_f32 v[64:65], v[26:27], v[26:27]
	v_pk_add_f32 v[36:37], v[36:37], v[38:39]
	v_pk_mul_f32 v[38:39], v[24:25], v[24:25]
	v_pk_add_f32 v[36:37], v[36:37], v[36:37] op_sel_hi:[0,1]
	v_pk_mov_b32 v[66:67], v[38:39], v[64:65] op_sel:[1,0]
	v_mov_b32_e32 v39, v65
	v_mul_f32_e32 v36, v20, v20
	v_pk_add_f32 v[38:39], v[66:67], v[38:39]
	v_pk_fma_f32 v[64:65], v[20:21], v[20:21], v[36:37] op_sel_hi:[1,1,0]
	v_mul_f32_e32 v36, v22, v22
	v_pk_add_f32 v[38:39], v[38:39], v[38:39] op_sel_hi:[0,1]
	v_pk_fma_f32 v[66:67], v[22:23], v[22:23], v[36:37] op_sel_hi:[1,1,0]
	v_mul_f32_e32 v64, v16, v16
	v_mul_f32_e32 v66, v17, v17
	v_mul_f32_e32 v38, v18, v18
	v_mul_f32_e32 v36, v19, v19
	v_pk_add_f32 v[64:65], v[64:65], v[66:67]
	v_pk_add_f32 v[36:37], v[38:39], v[36:37]
	v_pk_mul_f32 v[38:39], v[12:13], v[12:13]
	v_pk_add_f32 v[36:37], v[64:65], v[36:37]
	v_pk_mul_f32 v[64:65], v[14:15], v[14:15]
	v_pk_add_f32 v[36:37], v[36:37], v[36:37] op_sel_hi:[0,1]
	v_pk_mov_b32 v[66:67], v[38:39], v[64:65] op_sel:[1,0]
	v_mov_b32_e32 v39, v65
	v_mul_f32_e32 v36, v8, v8
	v_pk_add_f32 v[38:39], v[66:67], v[38:39]
	v_pk_fma_f32 v[64:65], v[8:9], v[8:9], v[36:37] op_sel_hi:[1,1,0]
	v_mul_f32_e32 v36, v10, v10
	v_pk_add_f32 v[38:39], v[38:39], v[38:39] op_sel_hi:[0,1]
	v_pk_fma_f32 v[66:67], v[10:11], v[10:11], v[36:37] op_sel_hi:[1,1,0]
	v_mul_f32_e32 v64, v4, v4
	v_mul_f32_e32 v66, v5, v5
	v_mul_f32_e32 v38, v6, v6
	v_mul_f32_e32 v36, v7, v7
	v_pk_add_f32 v[64:65], v[64:65], v[66:67]
	v_pk_add_f32 v[36:37], v[38:39], v[36:37]
	s_nop 0
	v_pk_add_f32 v[36:37], v[64:65], v[36:37]
	v_add_f32_e32 v36, v36, v37
	ds_bpermute_b32 v37, v74, v36
	s_waitcnt lgkmcnt(0)
; __device__ __forceinline__ unsigned pk2(float lo, float hi) { f32x2c v = {lo, hi}; return __builtin_bit_cast(unsigned, __builtin_convertvector(v, bf16x2c)); }
; __device__ __forceinline__ float row_rstd(const f32x4 (&v)[8]) {
;     float s = 0.f;
; #pragma unroll
;     for (int j = 0; j < 8; ++j) s += (v[j][0] * v[j][0] + v[j][1] * v[j][1]) + (v[j][2] * v[j][2] + v[j][3] * v[j][3]);
;     return rsqrtf(wave_sum(s) * (1.f / D) + 1e-6f);
; }
; __device__ __forceinline__ void row_store_bf16(bf16_t* p, int lane, const f32x4 (&v)[8]) {
; #pragma unroll
;     for (int j = 0; j < 8; ++j) { u32x2 w; w.x = pk2(v[j][0], v[j][1]); w.y = pk2(v[j][2], v[j][3]); *(u32x2*)(p + 256 * j + 4 * lane) = w; }
; }
; __device__ __forceinline__ void row_post1(const Params& p, int layer) {
;     ...
;         const float rs2 = row_rstd(x);
; #pragma unroll
;         for (int j = 0; j < 8; ++j) { const f32x4 g = *(const f32x4*)(g2 + 256 * j + 4 * lane); x[j] = x[j] * rs2 * g; }
;         row_store_bf16((bf16_t*)(ws + WS_HB) + (size_t)m * D, lane, x);
	v_add_f32_e32 v36, v36, v37
	ds_bpermute_b32 v37, v102, v36
	s_waitcnt lgkmcnt(0)
	v_add_f32_e32 v36, v36, v37
	ds_bpermute_b32 v37, v103, v36
	s_waitcnt lgkmcnt(0)
	v_add_f32_e32 v36, v36, v37
	ds_bpermute_b32 v37, v104, v36
	s_waitcnt lgkmcnt(0)
	v_add_f32_e32 v36, v36, v37
	ds_bpermute_b32 v37, v105, v36
	s_waitcnt lgkmcnt(0)
	v_add_f32_e32 v36, v36, v37
	ds_bpermute_b32 v37, v106, v36
	s_waitcnt lgkmcnt(0)
	v_add_f32_e32 v36, v36, v37
	v_fmamk_f32 v36, v36, 0x3a000000, v147
	v_cmp_gt_f32_e32 vcc, s29, v36
	v_mul_f32_e32 v37, 0x4b800000, v36
	s_nop 0
	v_cndmask_b32_e32 v36, v36, v37, vcc
	v_rsq_f32_e32 v36, v36
	s_nop 0
	v_mul_f32_e32 v37, 0x45800000, v36
	v_cndmask_b32_e32 v36, v36, v37, vcc
	v_pk_mul_f32 v[32:33], v[32:33], v[36:37] op_sel_hi:[1,0]
	v_pk_mul_f32 v[34:35], v[34:35], v[36:37] op_sel_hi:[1,0]
	v_pk_mul_f32 v[28:29], v[28:29], v[36:37] op_sel_hi:[1,0]
	v_pk_mul_f32 v[30:31], v[30:31], v[36:37] op_sel_hi:[1,0]
	v_pk_mul_f32 v[24:25], v[24:25], v[36:37] op_sel_hi:[1,0]
	v_pk_mul_f32 v[26:27], v[26:27], v[36:37] op_sel_hi:[1,0]
	v_pk_mul_f32 v[20:21], v[20:21], v[36:37] op_sel_hi:[1,0]
	v_pk_mul_f32 v[22:23], v[22:23], v[36:37] op_sel_hi:[1,0]
	v_pk_mul_f32 v[16:17], v[16:17], v[36:37] op_sel_hi:[1,0]
	v_pk_mul_f32 v[18:19], v[18:19], v[36:37] op_sel_hi:[1,0]
	v_pk_mul_f32 v[12:13], v[12:13], v[36:37] op_sel_hi:[1,0]
	v_pk_mul_f32 v[14:15], v[14:15], v[36:37] op_sel_hi:[1,0]
	v_pk_mul_f32 v[8:9], v[8:9], v[36:37] op_sel_hi:[1,0]
	v_pk_mul_f32 v[10:11], v[10:11], v[36:37] op_sel_hi:[1,0]
	v_pk_mul_f32 v[4:5], v[4:5], v[36:37] op_sel_hi:[1,0]
	v_pk_mul_f32 v[6:7], v[6:7], v[36:37] op_sel_hi:[1,0]
	v_pk_mul_f32 v[38:39], v[194:195], v[34:35]
	v_pk_mul_f32 v[64:65], v[192:193], v[32:33]
	v_pk_mul_f32 v[34:35], v[198:199], v[30:31]
	v_pk_mul_f32 v[32:33], v[196:197], v[28:29]
	v_pk_mul_f32 v[30:31], v[202:203], v[26:27]
	v_pk_mul_f32 v[28:29], v[200:201], v[24:25]
	v_pk_mul_f32 v[26:27], v[206:207], v[22:23]
	v_pk_mul_f32 v[24:25], v[204:205], v[20:21]
	v_pk_mul_f32 v[22:23], v[210:211], v[18:19]
	v_pk_mul_f32 v[20:21], v[208:209], v[16:17]
	v_pk_mul_f32 v[18:19], v[214:215], v[14:15]
	v_pk_mul_f32 v[16:17], v[212:213], v[12:13]
	v_pk_mul_f32 v[14:15], v[218:219], v[10:11]
	v_pk_mul_f32 v[12:13], v[216:217], v[8:9]
	v_pk_mul_f32 v[6:7], v[222:223], v[6:7]
	v_pk_mul_f32 v[4:5], v[220:221], v[4:5]
	v_lshl_add_u64 v[8:9], v[46:47], 0, s[6:7]
	v_cvt_pk_bf16_f32 v10, v64, v65
	v_cvt_pk_bf16_f32 v11, v38, v39
	global_store_dwordx2 v[8:9], v[10:11], off
	v_cvt_pk_bf16_f32 v10, v32, v33
	v_cvt_pk_bf16_f32 v11, v34, v35
	global_store_dwordx2 v[8:9], v[10:11], off offset:512
	v_cvt_pk_bf16_f32 v10, v28, v29
	v_cvt_pk_bf16_f32 v11, v30, v31
	global_store_dwordx2 v[8:9], v[10:11], off offset:1024
	v_cvt_pk_bf16_f32 v10, v24, v25
	v_cvt_pk_bf16_f32 v11, v26, v27
	global_store_dwordx2 v[8:9], v[10:11], off offset:1536
	v_cvt_pk_bf16_f32 v10, v20, v21
	v_cvt_pk_bf16_f32 v11, v22, v23
	global_store_dwordx2 v[8:9], v[10:11], off offset:2048
	v_cvt_pk_bf16_f32 v10, v16, v17
	v_cvt_pk_bf16_f32 v11, v18, v19
	global_store_dwordx2 v[8:9], v[10:11], off offset:2560
	v_cvt_pk_bf16_f32 v10, v12, v13
	v_cvt_pk_bf16_f32 v11, v14, v15
	v_cvt_pk_bf16_f32 v4, v4, v5
	v_cvt_pk_bf16_f32 v5, v6, v7
	s_cselect_b64 s[6:7], -1, 0
	global_store_dwordx2 v[8:9], v[10:11], off offset:3072
	global_store_dwordx2 v[8:9], v[4:5], off offset:3584
